# scan compute waves: stale s_waitcnt vmcnt(0) at the top of every chunk step (left from the flat-store era; waited for the previous step's 16 output store acks) removed
# baseline (speedup 1.0000x reference)
; #define GAS __attribute__((address_space(1)))
; #define MFMA16(a, b, c) __builtin_amdgcn_mfma_f32_16x16x32_f16((a), (b), (c), 0, 0, 0)
; #define LD_A(F, ti_) do { _Pragma("unroll") for (int kk = 0; kk < 4; ++kk) { const h16* kp = kn + (16 * (ti_) + fr) * 136 + 32 * kk + 4 * g; const h16* qp = qn + (16 * (ti_) + fr) * 136 + 32 * kk + 4 * g; \
;                     F[2 * kk] = cat8(*(const h16x4*)kp, *(const h16x4*)(kp + 16)); F[2 * kk + 1] = cat8(*(const h16x4*)qp, *(const h16x4*)(qp + 16)); } } while (0)
; __device__ __forceinline__ void phase_scan(h16* Pdn, const h16* Tg, const h16* qkg, const float* gcg, const float* betag, const float* s2g, unsigned char* ldsb) {
;     ...
;             const h16* B = (const h16*)ldsb + (n & 1) * BUFH;
;             const h16* qn = B + OQ; const h16* kn = B + OK_; const h16* Tm = B + OT; const h16* qkm = B + OQK; const h16* vbs = B + OV;
;             const float* gcs = (const float*)(B + OSC); const float* bts = gcs + 64; const float* s2s = gcs + 128;
;             {
;                 GAS h16* ob = (GAS h16*)(Pdn + (tok0 * 4096 + 2048 + h * 128 + 64 * s));
;                 const float e_last = gcs[63];
;                 h16x8 Sf[4];
; #pragma unroll
;                 for (int kk = 0; kk < 4; ++kk)
; #pragma unroll
;                     for (int rg = 0; rg < 4; ++rg) { Sf[kk][rg] = (h16)S[2 * kk][rg]; Sf[kk][4 + rg] = (h16)S[2 * kk + 1][rg]; }
;     ...
;                 h16x8 F0[8], F1[8];
;                 f32x4 gc0, bt0, gc1 = {0.f, 0.f, 0.f, 0.f}, bt1 = {0.f, 0.f, 0.f, 0.f}; h16x4 vb0, vb1 = {0, 0, 0, 0};
;                 LD_A(F0, 0); LD_S(gc0, bt0, vb0, 0);
;                 f32x4 R[4], O[4];
; #pragma unroll
;                 for (int ti = 0; ti < 4; ++ti) {
;                     if (ti < 3) { LD_A(F1, ti + 1); LD_S(gc1, bt1, vb1, ti + 1); } else LD_T(F1, Tm);
;                     __builtin_amdgcn_sched_barrier(0);
;                     f32x4 ka = {0.f, 0.f, 0.f, 0.f}, qa = {0.f, 0.f, 0.f, 0.f};
; #pragma unroll
;                     for (int kk = 0; kk < 4; ++kk) { ka = MFMA16(F0[2 * kk], Sf[kk], ka); qa = MFMA16(F0[2 * kk + 1], Sf[kk], qa); }
; #pragma unroll
;                     for (int rg = 0; rg < 4; ++rg) { R[ti][rg] = (float)vb0[rg] - bt0[rg] * ka[rg]; O[ti][rg] = gc0[rg] * qa[rg]; }
.LBB0_247:
	s_bitcmp1_b32 s7, 0
	s_cselect_b32 s0, 0xf300, 0
	s_add_i32 s9, s0, 0
	s_lshl_b64 s[0:1], s[12:13], 1
	s_add_u32 s0, s86, s0
	v_lshl_add_u32 v179, v171, 1, s9
	s_addc_u32 s1, s87, s1
	v_add_u32_e32 v70, v179, v177
	s_lshl_b32 s10, s6, 1
	v_add_u32_e32 v50, 0x4000, v70
	s_add_i32 s10, s9, s10
	v_mov_b32_e32 v32, s9
	ds_read2_b64 v[34:37], v50 offset0:128 offset1:132
	ds_read2_b64 v[38:41], v70 offset1:4
	ds_read2_b64 v[42:45], v50 offset0:136 offset1:140
	ds_read2_b64 v[58:61], v70 offset0:8 offset1:12
	ds_read2_b64 v[74:77], v50 offset0:144 offset1:148
	ds_read2_b64 v[78:81], v70 offset0:16 offset1:20
	ds_read2_b64 v[82:85], v50 offset0:152 offset1:156
	ds_read2_b64 v[86:89], v70 offset0:24 offset1:28
	v_lshl_add_u32 v136, v171, 2, s9
	v_add3_u32 v50, s10, v172, v178
	v_add3_u32 v137, s10, v178, v172
	v_add_u32_e32 v71, 0x1000, v70
	v_add_u32_e32 v70, 0x5000, v70
	ds_read_b32 v32, v32 offset:61692
	ds_read_b128 v[90:93], v136 offset:61440
	ds_read_b128 v[54:57], v136 offset:61696
	ds_read_b128 v[94:97], v136 offset:61504
	ds_read_b64_tr_b16 v[108:109], v50 offset:53248
	ds_read_b128 v[50:53], v136 offset:61760
	ds_read_b64_tr_b16 v[106:107], v137 offset:55296
	ds_read2_b64 v[98:101], v71 offset0:56 offset1:60
	ds_read2_b64 v[102:105], v70 offset0:184 offset1:188
	ds_read2_b64 v[110:113], v71 offset0:48 offset1:52
	ds_read2_b64 v[116:119], v70 offset0:176 offset1:180
	ds_read2_b64 v[120:123], v71 offset0:40 offset1:44
	ds_read2_b64 v[124:127], v70 offset0:168 offset1:172
	ds_read2_b64 v[128:131], v71 offset0:32 offset1:36
	ds_read2_b64 v[132:135], v70 offset0:160 offset1:164
	v_cvt_pk_f16_f32 v49, v10, v11
	v_cvt_pk_f16_f32 v48, v8, v9
	v_cvt_pk_f16_f32 v47, v14, v15
	v_cvt_pk_f16_f32 v46, v12, v13
	v_cvt_pk_f16_f32 v65, v2, v3
	v_cvt_pk_f16_f32 v64, v0, v1
	v_cvt_pk_f16_f32 v63, v6, v7
	v_cvt_pk_f16_f32 v62, v4, v5
	v_cvt_pk_f16_f32 v69, v22, v23
	v_cvt_pk_f16_f32 v68, v20, v21
	v_cvt_pk_f16_f32 v67, v18, v19
	v_cvt_pk_f16_f32 v66, v16, v17
	v_cvt_pk_f16_f32 v73, v30, v31
	v_cvt_pk_f16_f32 v72, v28, v29
	v_cvt_pk_f16_f32 v71, v26, v27
	v_cvt_pk_f16_f32 v70, v24, v25
	v_add_u32_e32 v180, v136, v176
	s_waitcnt lgkmcnt(0)
	v_mfma_f32_16x16x32_f16 v[34:37], v[34:37], v[46:49], 0
	v_add_u32_e32 v181, v180, v177
	v_mfma_f32_16x16x32_f16 v[38:41], v[38:41], v[46:49], 0
	v_mfma_f32_16x16x32_f16 v[34:37], v[42:45], v[62:65], v[34:37]
	v_mfma_f32_16x16x32_f16 v[38:41], v[58:61], v[62:65], v[38:41]
	ds_read_b128 v[42:45], v136 offset:61568
	ds_read_b128 v[58:61], v136 offset:61824
	ds_read_b64_tr_b16 v[114:115], v137 offset:57344
	v_mfma_f32_16x16x32_f16 v[34:37], v[74:77], v[66:69], v[34:37]
	v_mfma_f32_16x16x32_f16 v[38:41], v[78:81], v[66:69], v[38:41]
	v_mfma_f32_16x16x32_f16 v[74:77], v[82:85], v[70:73], v[34:37]
	v_mfma_f32_16x16x32_f16 v[34:37], v[86:89], v[70:73], v[38:41]
	s_nop 5
	v_add_u32_e32 v38, 0x2000, v181
	v_add_u32_e32 v39, 0x6000, v181
	v_pk_mul_f32 v[36:37], v[92:93], v[36:37]
	v_pk_mul_f32 v[34:35], v[90:91], v[34:35]
	ds_read2_b64 v[90:93], v38 offset0:88 offset1:92
	ds_read2_b64 v[86:89], v39 offset0:216 offset1:220
	ds_read2_b64 v[204:207], v38 offset0:80 offset1:84
	ds_read2_b64 v[208:211], v39 offset0:208 offset1:212
	ds_read2_b64 v[212:215], v38 offset0:72 offset1:76
	ds_read2_b64 v[216:219], v39 offset0:200 offset1:204
	ds_read2_b64 v[220:223], v38 offset0:64 offset1:68
	ds_read2_b64 v[224:227], v39 offset0:192 offset1:196
	v_mfma_f32_16x16x32_f16 v[38:41], v[132:135], v[46:49], 0
	v_mfma_f32_16x16x32_f16 v[78:81], v[128:131], v[46:49], 0
	v_mfma_f32_16x16x32_f16 v[38:41], v[124:127], v[62:65], v[38:41]
	v_mfma_f32_16x16x32_f16 v[78:81], v[120:123], v[62:65], v[78:81]
	v_mfma_f32_16x16x32_f16 v[38:41], v[116:119], v[66:69], v[38:41]
	v_mfma_f32_16x16x32_f16 v[78:81], v[110:113], v[66:69], v[78:81]
	v_mfma_f32_16x16x32_f16 v[82:85], v[102:105], v[70:73], v[38:41]
	v_mfma_f32_16x16x32_f16 v[38:41], v[98:101], v[70:73], v[78:81]
	ds_read_b128 v[118:121], v136 offset:61632
	s_nop 4
	ds_read_b128 v[78:81], v136 offset:61888
	ds_read_b64_tr_b16 v[116:117], v137 offset:59392
	v_pk_mul_f32 v[38:39], v[94:95], v[38:39]
	v_add_u32_e32 v94, 0x3000, v181
	v_add_u32_e32 v95, 0x7000, v181
	ds_read2_b64 v[122:125], v94 offset0:120 offset1:124
	ds_read2_b64 v[228:231], v95 offset0:248 offset1:252
	ds_read2_b64 v[232:235], v94 offset0:112 offset1:116
	ds_read2_b64 v[236:239], v95 offset0:240 offset1:244
	ds_read2_b64 v[240:243], v94 offset0:104 offset1:108
	ds_read2_b64 v[244:247], v95 offset0:232 offset1:236
	ds_read2_b64 v[248:251], v94 offset0:96 offset1:100
	ds_read2_b64 v[196:199], v95 offset0:224 offset1:228
	v_pk_mul_f32 v[40:41], v[96:97], v[40:41]
	s_waitcnt lgkmcnt(12)
	v_mfma_f32_16x16x32_f16 v[98:101], v[220:223], v[46:49], 0
	v_add_u32_e32 v130, v180, v173
	v_add_u32_e32 v102, 0x9800, v130
	v_add_u32_e32 v126, 0x9000, v130
	s_waitcnt lgkmcnt(11)
	v_mfma_f32_16x16x32_f16 v[94:97], v[224:227], v[46:49], 0
	v_add_u32_e32 v134, 0x8800, v130
	v_mfma_f32_16x16x32_f16 v[98:101], v[212:215], v[62:65], v[98:101]
	v_mfma_f32_16x16x32_f16 v[94:97], v[216:219], v[62:65], v[94:97]
	v_mfma_f32_16x16x32_f16 v[98:101], v[204:207], v[66:69], v[98:101]
	v_mfma_f32_16x16x32_f16 v[94:97], v[208:211], v[66:69], v[94:97]
	v_mfma_f32_16x16x32_f16 v[90:93], v[90:93], v[70:73], v[98:101]
	v_mfma_f32_16x16x32_f16 v[86:89], v[86:89], v[70:73], v[94:97]
	s_nop 5
	v_add_u32_e32 v94, 0xa000, v130
	v_pk_mul_f32 v[44:45], v[44:45], v[92:93]
	v_pk_mul_f32 v[42:43], v[42:43], v[90:91]
	ds_read2_b64 v[90:93], v94 offset0:104 offset1:108
	ds_read2_b64 v[94:97], v94 offset0:96 offset1:100
	ds_read2_b64 v[98:101], v102 offset0:72 offset1:76
	ds_read2_b64 v[102:105], v102 offset0:64 offset1:68
	ds_read2_b64 v[110:113], v126 offset0:40 offset1:44
	ds_read2_b64 v[126:129], v126 offset0:32 offset1:36
	ds_read2_b64 v[130:133], v134 offset0:8 offset1:12
	ds_read2_b64 v[134:137], v134 offset1:4
	s_waitcnt lgkmcnt(8)
; #define MFMA16(a, b, c) __builtin_amdgcn_mfma_f32_16x16x32_f16((a), (b), (c), 0, 0, 0)
; #define CP_F(D, S_) do { _Pragma("unroll") for (int q = 0; q < 8; ++q) D[q] = S_[q]; } while (0)
; __device__ __forceinline__ void phase_scan(h16* Pdn, const h16* Tg, const h16* qkg, const float* gcg, const float* betag, const float* s2g, unsigned char* ldsb) {
;     ...
;                 for (int ti = 0; ti < 4; ++ti) {
;                     if (ti < 3) { LD_A(F1, ti + 1); LD_S(gc1, bt1, vb1, ti + 1); } else LD_T(F1, Tm);
;                     __builtin_amdgcn_sched_barrier(0);
;                     f32x4 ka = {0.f, 0.f, 0.f, 0.f}, qa = {0.f, 0.f, 0.f, 0.f};
; #pragma unroll
;                     for (int kk = 0; kk < 4; ++kk) { ka = MFMA16(F0[2 * kk], Sf[kk], ka); qa = MFMA16(F0[2 * kk + 1], Sf[kk], qa); }
; #pragma unroll
;                     for (int rg = 0; rg < 4; ++rg) { R[ti][rg] = (float)vb0[rg] - bt0[rg] * ka[rg]; O[ti][rg] = gc0[rg] * qa[rg]; }
;                     CP_F(F0, F1); gc0 = gc1; bt0 = bt1; vb0 = vb1;
;                 }
;                 h16x8 Rf[2];
; #pragma unroll
;                 for (int k2 = 0; k2 < 2; ++k2)
; #pragma unroll
;                     for (int rg = 0; rg < 4; ++rg) { Rf[k2][rg] = (h16)R[2 * k2][rg]; Rf[k2][4 + rg] = (h16)R[2 * k2 + 1][rg]; }
;                 LD_T(F1, qkm);
;                 __builtin_amdgcn_sched_barrier(0);
;                 f32x4 Vn[4];
; #pragma unroll
;                 for (int ti = 0; ti < 4; ++ti) {
;                     f32x4 acc = {0.f, 0.f, 0.f, 0.f};
; #pragma unroll
;                     for (int k2 = 0; k2 < 2; ++k2) acc = MFMA16(F0[2 * ti + k2], Rf[k2], acc);
;                     Vn[ti] = acc;
;                 }
;                 CP_F(F0, F1);
;                 h16x8 Vf[2], V2f[2];
; #pragma unroll
;                 for (int k2 = 0; k2 < 2; ++k2) {
;                     const f32x4 gca = *(const f32x4*)(s2s + 32 * k2 + 4 * g), gcb = *(const f32x4*)(s2s + 32 * k2 + 16 + 4 * g);
; #pragma unroll
;                     for (int rg = 0; rg < 4; ++rg) {
;                         Vf[k2][rg] = (h16)Vn[2 * k2][rg]; Vf[k2][4 + rg] = (h16)Vn[2 * k2 + 1][rg];
;                         V2f[k2][rg] = (h16)(Vn[2 * k2][rg] * gca[rg]); V2f[k2][4 + rg] = (h16)(Vn[2 * k2 + 1][rg] * gcb[rg]);
;                     }
;                 }
	v_mfma_f32_16x16x32_f16 v[196:199], v[196:199], v[46:49], 0
	v_mfma_f32_16x16x32_f16 v[46:49], v[248:251], v[46:49], 0
	v_mfma_f32_16x16x32_f16 v[196:199], v[244:247], v[62:65], v[196:199]
	v_mfma_f32_16x16x32_f16 v[46:49], v[240:243], v[62:65], v[46:49]
	v_mfma_f32_16x16x32_f16 v[62:65], v[236:239], v[66:69], v[196:199]
	v_mfma_f32_16x16x32_f16 v[46:49], v[232:235], v[66:69], v[46:49]
	v_cvt_f32_f16_e32 v66, v108
	v_cvt_f32_f16_sdwa v67, v108 dst_sel:DWORD dst_unused:UNUSED_PAD src0_sel:WORD_1
	v_pk_fma_f32 v[54:55], v[54:55], v[74:75], v[66:67] neg_lo:[1,0,0] neg_hi:[1,0,0]
	s_nop 0
	v_cvt_pk_f16_f32 v66, v54, v55
	v_cvt_f32_f16_e32 v54, v106
	v_cvt_f32_f16_sdwa v55, v106 dst_sel:DWORD dst_unused:UNUSED_PAD src0_sel:WORD_1
	v_mfma_f32_16x16x32_f16 v[62:65], v[228:231], v[70:73], v[62:65]
	v_fma_f32 v50, -v50, v82, v54
	v_fma_f32 v51, -v51, v83, v55
	v_cvt_pk_f16_f32 v68, v50, v51
	v_cvt_f32_f16_e32 v50, v109
	v_cvt_f32_f16_sdwa v51, v109 dst_sel:DWORD dst_unused:UNUSED_PAD src0_sel:WORD_1
	v_cvt_f32_f16_e32 v54, v115
	v_cvt_f32_f16_sdwa v55, v115 dst_sel:DWORD dst_unused:UNUSED_PAD src0_sel:WORD_1
	v_mfma_f32_16x16x32_f16 v[46:49], v[122:125], v[70:73], v[46:49]
	v_fma_f32 v50, -v56, v76, v50
	v_fma_f32 v51, -v57, v77, v51
	v_pk_fma_f32 v[54:55], v[60:61], v[88:89], v[54:55] neg_lo:[1,0,0] neg_hi:[1,0,0]
	v_cvt_pk_f16_f32 v67, v50, v51
	v_cvt_f32_f16_e32 v50, v107
	v_cvt_f32_f16_sdwa v51, v107 dst_sel:DWORD dst_unused:UNUSED_PAD src0_sel:WORD_1
	s_nop 1
	v_pk_mul_f32 v[48:49], v[120:121], v[48:49]
	v_pk_mul_f32 v[46:47], v[118:119], v[46:47]
	v_pk_fma_f32 v[50:51], v[52:53], v[84:85], v[50:51] neg_lo:[1,0,0] neg_hi:[1,0,0]
	s_nop 0
	v_cvt_pk_f16_f32 v69, v50, v51
	v_cvt_f32_f16_e32 v50, v114
	v_cvt_f32_f16_sdwa v51, v114 dst_sel:DWORD dst_unused:UNUSED_PAD src0_sel:WORD_1
	v_cvt_f32_f16_e32 v52, v116
	v_cvt_f32_f16_sdwa v53, v116 dst_sel:DWORD dst_unused:UNUSED_PAD src0_sel:WORD_1
	v_pk_fma_f32 v[50:51], v[58:59], v[86:87], v[50:51] neg_lo:[1,0,0] neg_hi:[1,0,0]
	s_nop 0
	v_cvt_pk_f16_f32 v50, v50, v51
	v_cvt_pk_f16_f32 v51, v54, v55
	v_cvt_f32_f16_e32 v54, v117
	v_cvt_f32_f16_sdwa v55, v117 dst_sel:DWORD dst_unused:UNUSED_PAD src0_sel:WORD_1
	v_pk_fma_f32 v[52:53], v[78:79], v[62:63], v[52:53] neg_lo:[1,0,0] neg_hi:[1,0,0]
	v_pk_fma_f32 v[54:55], v[80:81], v[64:65], v[54:55] neg_lo:[1,0,0] neg_hi:[1,0,0]
	v_cvt_pk_f16_f32 v52, v52, v53
	v_cvt_pk_f16_f32 v53, v54, v55
	v_add_u32_e32 v54, v179, v173
	v_add_u32_e32 v55, 0xa800, v54
	ds_read2_b64 v[118:121], v55 offset0:128 offset1:132
	ds_read2_b64 v[122:125], v55 offset0:136 offset1:140
	v_add_u32_e32 v55, 0xb000, v54
	ds_read2_b64 v[114:117], v55 offset0:160 offset1:164
	ds_read2_b64 v[106:109], v55 offset0:168 offset1:172
	v_add_u32_e32 v55, 0xb800, v54
	v_add_u32_e32 v54, 0xc000, v54
	ds_read2_b64 v[86:89], v55 offset0:192 offset1:196
	ds_read2_b64 v[82:85], v55 offset0:200 offset1:204
	ds_read2_b64 v[62:65], v54 offset0:224 offset1:228
	ds_read2_b64 v[58:61], v54 offset0:232 offset1:236
	s_waitcnt lgkmcnt(8)
	v_mfma_f32_16x16x32_f16 v[54:57], v[134:137], v[66:69], 0
	v_mfma_f32_16x16x32_f16 v[70:73], v[126:129], v[66:69], 0
	v_mfma_f32_16x16x32_f16 v[74:77], v[102:105], v[66:69], 0
	v_add3_u32 v104, s9, v178, v174
	v_mfma_f32_16x16x32_f16 v[66:69], v[94:97], v[66:69], 0
	v_mfma_f32_16x16x32_f16 v[66:69], v[90:93], v[50:53], v[66:69]
	v_add_u32_e32 v92, v179, v175
	v_mfma_f32_16x16x32_f16 v[54:57], v[130:133], v[50:53], v[54:57]
	v_mfma_f32_16x16x32_f16 v[70:73], v[110:113], v[50:53], v[70:73]
	s_nop 4
	v_cvt_pk_f16_f32 v128, v66, v67
	s_nop 0
	v_cvt_pk_f16_f32 v110, v54, v55
	v_cvt_pk_f16_f32 v111, v56, v57
	v_mfma_f32_16x16x32_f16 v[74:77], v[98:101], v[50:53], v[74:77]
	ds_read_b128 v[50:53], v92 offset:61952
	ds_read_b128 v[78:81], v92 offset:62016
	v_cvt_pk_f16_f32 v113, v72, v73
	v_cvt_pk_f16_f32 v112, v70, v71
	v_cvt_pk_f16_f32 v129, v68, v69
	s_waitcnt lgkmcnt(1)
	v_pk_mul_f32 v[90:91], v[56:57], v[52:53]
	v_mul_f32_e32 v51, v55, v51
	v_fma_mixlo_f16 v93, v54, v50, 0
	v_pk_mov_b32 v[50:51], v[50:51], v[90:91] op_sel:[1,0]
	s_waitcnt lgkmcnt(0)
	v_pk_mul_f32 v[90:91], v[70:71], v[78:79]
	v_mul_f32_e32 v80, v72, v80
	v_pk_mov_b32 v[90:91], v[90:91], v[80:81] op_sel:[1,0]
	v_pk_mov_b32 v[54:55], v[56:57], v[70:71] op_sel:[1,0]
	v_pk_mov_b32 v[52:53], v[52:53], v[78:79] op_sel:[1,0]
	v_cvt_pk_f16_f32 v80, v90, v91
	v_pk_mul_f32 v[52:53], v[54:55], v[52:53]
	v_cvt_pk_f16_f32 v51, v50, v51
	v_cvt_pk_f16_f32 v52, v52, v53
	v_lshrrev_b32_e32 v53, 16, v80
	v_fma_mixhi_f16 v53, v73, v81, 0
	ds_read_b128 v[54:57], v92 offset:62080
	ds_read_b128 v[70:73], v92 offset:62144
	v_pack_b32_f16 v50, v93, v51
	v_alignbit_b32 v51, v52, v51, 16
	v_alignbit_b32 v52, v80, v52, 16
	s_waitcnt lgkmcnt(1)
	v_pk_mul_f32 v[78:79], v[76:77], v[56:57]
	v_mul_f32_e32 v55, v75, v55
	v_fma_mixlo_f16 v80, v74, v54, 0
	v_pk_mov_b32 v[54:55], v[54:55], v[78:79] op_sel:[1,0]
	s_waitcnt lgkmcnt(0)
; #define LDS_BARRIER() do { asm volatile("s_waitcnt lgkmcnt(0)" ::: "memory"); __builtin_amdgcn_s_barrier(); asm volatile("" ::: "memory"); } while (0)
; #define MFMA16(a, b, c) __builtin_amdgcn_mfma_f32_16x16x32_f16((a), (b), (c), 0, 0, 0)
; #define CP_F(D, S_) do { _Pragma("unroll") for (int q = 0; q < 8; ++q) D[q] = S_[q]; } while (0)
; __device__ __forceinline__ void phase_scan(h16* Pdn, const h16* Tg, const h16* qkg, const float* gcg, const float* betag, const float* s2g, unsigned char* ldsb) {
;     ...
;                 h16x8 Vf[2], V2f[2];
; #pragma unroll
;                 for (int k2 = 0; k2 < 2; ++k2) {
;                     const f32x4 gca = *(const f32x4*)(s2s + 32 * k2 + 4 * g), gcb = *(const f32x4*)(s2s + 32 * k2 + 16 + 4 * g);
; #pragma unroll
;                     for (int rg = 0; rg < 4; ++rg) {
;                         Vf[k2][rg] = (h16)Vn[2 * k2][rg]; Vf[k2][4 + rg] = (h16)Vn[2 * k2 + 1][rg];
;                         V2f[k2][rg] = (h16)(Vn[2 * k2][rg] * gca[rg]); V2f[k2][4 + rg] = (h16)(Vn[2 * k2 + 1][rg] * gcb[rg]);
;                     }
;                 }
;                 LD_K(F1, 0);
;                 __builtin_amdgcn_sched_barrier(0);
; #pragma unroll
;                 for (int ti = 0; ti < 4; ++ti) {
; #pragma unroll
;                     for (int k2 = 0; k2 < 2; ++k2) O[ti] = MFMA16(F0[2 * ti + k2], Vf[k2], O[ti]);
; #pragma unroll
;                     for (int rg = 0; rg < 4; ++rg) {
;                         const int i = 16 * ti + 4 * g + rg;
;                         ob[i * 4096 + 16 * w + fr] = (h16)O[ti][rg];
;                     }
;                 }
;                 CP_F(F0, F1);
;                 LD_K(F1, 4);
;                 __builtin_amdgcn_sched_barrier(0);
; #pragma unroll
;                 for (int t = 0; t < 4; ++t) {
;                     f32x4 acc = S[t] * e_last;
; #pragma unroll
;                     for (int k2 = 0; k2 < 2; ++k2) acc = MFMA16(F0[2 * t + k2], V2f[k2], acc);
;                     S[t] = acc;
;                 }
;                 __builtin_amdgcn_sched_barrier(0);
; #pragma unroll
;                 for (int t = 0; t < 4; ++t) {
;                     f32x4 acc = S[4 + t] * e_last;
; #pragma unroll
;                     for (int k2 = 0; k2 < 2; ++k2) acc = MFMA16(F1[2 * t + k2], V2f[k2], acc);
;                     S[4 + t] = acc;
;                 }
;     ...
;             }
;             LDS_BARRIER();
	v_pk_mul_f32 v[78:79], v[66:67], v[70:71]
	v_mul_f32_e32 v72, v68, v72
	v_pk_mov_b32 v[78:79], v[78:79], v[72:73] op_sel:[1,0]
	v_pk_mov_b32 v[66:67], v[76:77], v[66:67] op_sel:[1,0]
	v_pk_mov_b32 v[56:57], v[56:57], v[70:71] op_sel:[1,0]
	v_cvt_pk_f16_f32 v72, v78, v79
	v_pk_mul_f32 v[56:57], v[66:67], v[56:57]
	v_cvt_pk_f16_f32 v55, v54, v55
	v_cvt_pk_f16_f32 v56, v56, v57
	v_lshrrev_b32_e32 v57, 16, v72
	v_pack_b32_f16 v54, v80, v55
	v_cvt_pk_f16_f32 v127, v76, v77
	v_cvt_pk_f16_f32 v126, v74, v75
	v_alignbit_b32 v55, v56, v55, 16
	v_alignbit_b32 v56, v72, v56, 16
	v_fma_mixhi_f16 v57, v69, v73, 0
	ds_read_b64_tr_b16 v[76:77], v104 offset:21760
	ds_read_b64_tr_b16 v[74:75], v104 offset:17408
	ds_read_b64_tr_b16 v[66:67], v104 offset:17440
	ds_read_b64_tr_b16 v[78:79], v104 offset:26112
	ds_read_b64_tr_b16 v[80:81], v104 offset:30464
	ds_read_b64_tr_b16 v[68:69], v104 offset:21792
	ds_read_b64_tr_b16 v[70:71], v104 offset:26144
	ds_read_b64_tr_b16 v[72:73], v104 offset:30496
	ds_read_b64_tr_b16 v[90:91], v104 offset:17472
	ds_read_b64_tr_b16 v[92:93], v104 offset:21824
	ds_read_b64_tr_b16 v[94:95], v104 offset:26176
	ds_read_b64_tr_b16 v[96:97], v104 offset:30528
	ds_read_b64_tr_b16 v[98:99], v104 offset:17504
	ds_read_b64_tr_b16 v[100:101], v104 offset:21856
	ds_read_b64_tr_b16 v[102:103], v104 offset:26208
	ds_read_b64_tr_b16 v[104:105], v104 offset:30560
	v_mfma_f32_16x16x32_f16 v[34:37], v[118:121], v[110:113], v[34:37]
	v_lshl_add_u64 v[118:119], v[138:139], 1, s[0:1]
	v_mfma_f32_16x16x32_f16 v[34:37], v[122:125], v[126:129], v[34:37]
	s_nop 7
	v_cvt_f16_f32_e32 v34, v34
	v_cvt_f16_f32_e32 v36, v36
	global_store_short v[118:119], v34, off
	v_cvt_f16_f32_e32 v118, v35
	v_lshl_add_u64 v[34:35], v[140:141], 1, s[0:1]
	global_store_short v[34:35], v118, off
	v_lshl_add_u64 v[34:35], v[142:143], 1, s[0:1]
	global_store_short v[34:35], v36, off
	v_cvt_f16_f32_e32 v36, v37
	v_lshl_add_u64 v[34:35], v[144:145], 1, s[0:1]
	global_store_short v[34:35], v36, off
	v_mfma_f32_16x16x32_f16 v[34:37], v[114:117], v[110:113], v[38:41]
	v_mfma_f32_16x16x32_f16 v[34:37], v[106:109], v[126:129], v[34:37]
	s_nop 1
	v_lshl_add_u64 v[38:39], v[146:147], 1, s[0:1]
	s_nop 4
	v_cvt_f16_f32_e32 v34, v34
	v_cvt_f16_f32_e32 v36, v36
	global_store_short v[38:39], v34, off
	v_cvt_f16_f32_e32 v38, v35
	v_lshl_add_u64 v[34:35], v[148:149], 1, s[0:1]
	global_store_short v[34:35], v38, off
	v_lshl_add_u64 v[34:35], v[150:151], 1, s[0:1]
	global_store_short v[34:35], v36, off
	v_cvt_f16_f32_e32 v36, v37
	v_lshl_add_u64 v[34:35], v[152:153], 1, s[0:1]
	v_lshl_add_u64 v[38:39], v[154:155], 1, s[0:1]
	global_store_short v[34:35], v36, off
	v_mfma_f32_16x16x32_f16 v[34:37], v[86:89], v[110:113], v[42:45]
	v_add3_u32 v88, s9, v174, v178
	v_mfma_f32_16x16x32_f16 v[34:37], v[82:85], v[126:129], v[34:37]
	s_nop 7
	v_cvt_f16_f32_e32 v34, v34
	v_cvt_f16_f32_e32 v36, v36
	global_store_short v[38:39], v34, off
	v_cvt_f16_f32_e32 v38, v35
	v_lshl_add_u64 v[34:35], v[156:157], 1, s[0:1]
	global_store_short v[34:35], v38, off
	v_lshl_add_u64 v[34:35], v[158:159], 1, s[0:1]
	global_store_short v[34:35], v36, off
	v_cvt_f16_f32_e32 v36, v37
	v_lshl_add_u64 v[34:35], v[160:161], 1, s[0:1]
	v_lshl_add_u64 v[38:39], v[162:163], 1, s[0:1]
	global_store_short v[34:35], v36, off
	v_mfma_f32_16x16x32_f16 v[34:37], v[62:65], v[110:113], v[46:49]
	v_mfma_f32_16x16x32_f16 v[34:37], v[58:61], v[126:129], v[34:37]
	s_nop 7
	v_cvt_f16_f32_e32 v34, v34
	v_cvt_f16_f32_e32 v36, v36
	global_store_short v[38:39], v34, off
	v_cvt_f16_f32_e32 v38, v35
	v_lshl_add_u64 v[34:35], v[164:165], 1, s[0:1]
	global_store_short v[34:35], v38, off
	v_lshl_add_u64 v[34:35], v[166:167], 1, s[0:1]
	global_store_short v[34:35], v36, off
	v_cvt_f16_f32_e32 v36, v37
	v_lshl_add_u64 v[34:35], v[168:169], 1, s[0:1]
	global_store_short v[34:35], v36, off
	ds_read_b64_tr_b16 v[36:37], v88 offset:21888
	ds_read_b64_tr_b16 v[34:35], v88 offset:17536
	ds_read_b64_tr_b16 v[38:39], v88 offset:17568
	ds_read_b64_tr_b16 v[42:43], v88 offset:26240
	ds_read_b64_tr_b16 v[44:45], v88 offset:30592
	ds_read_b64_tr_b16 v[40:41], v88 offset:21920
	ds_read_b64_tr_b16 v[46:47], v88 offset:26272
	ds_read_b64_tr_b16 v[48:49], v88 offset:30624
	ds_read_b64_tr_b16 v[58:59], v88 offset:17600
	ds_read_b64_tr_b16 v[60:61], v88 offset:21952
	ds_read_b64_tr_b16 v[62:63], v88 offset:26304
	ds_read_b64_tr_b16 v[64:65], v88 offset:30656
	ds_read_b64_tr_b16 v[82:83], v88 offset:17632
	ds_read_b64_tr_b16 v[84:85], v88 offset:21984
	ds_read_b64_tr_b16 v[86:87], v88 offset:26336
	ds_read_b64_tr_b16 v[88:89], v88 offset:30688
	v_pk_mul_f32 v[14:15], v[14:15], v[32:33] op_sel_hi:[1,0]
	v_pk_mul_f32 v[12:13], v[12:13], v[32:33] op_sel_hi:[1,0]
	v_pk_mul_f32 v[10:11], v[10:11], v[32:33] op_sel_hi:[1,0]
	v_pk_mul_f32 v[8:9], v[8:9], v[32:33] op_sel_hi:[1,0]
	v_pk_mul_f32 v[6:7], v[6:7], v[32:33] op_sel_hi:[1,0]
	v_pk_mul_f32 v[4:5], v[4:5], v[32:33] op_sel_hi:[1,0]
	v_pk_mul_f32 v[2:3], v[2:3], v[32:33] op_sel_hi:[1,0]
	v_pk_mul_f32 v[0:1], v[0:1], v[32:33] op_sel_hi:[1,0]
	s_waitcnt lgkmcnt(14)
	v_mfma_f32_16x16x32_f16 v[12:15], v[74:77], v[50:53], v[12:15]
	v_mfma_f32_16x16x32_f16 v[8:11], v[66:69], v[50:53], v[8:11]
	v_mfma_f32_16x16x32_f16 v[4:7], v[90:93], v[50:53], v[4:7]
	v_mfma_f32_16x16x32_f16 v[0:3], v[98:101], v[50:53], v[0:3]
	v_mfma_f32_16x16x32_f16 v[12:15], v[78:81], v[54:57], v[12:15]
	v_mfma_f32_16x16x32_f16 v[8:11], v[70:73], v[54:57], v[8:11]
	v_mfma_f32_16x16x32_f16 v[4:7], v[94:97], v[54:57], v[4:7]
	v_mfma_f32_16x16x32_f16 v[0:3], v[102:105], v[54:57], v[0:3]
	v_mul_f32_e64 v18, v18, v32
	v_mul_f32_e64 v19, v19, v32
	v_pk_mul_f32 v[16:17], v[16:17], v[32:33] op_sel_hi:[1,0]
	v_pk_mul_f32 v[22:23], v[22:23], v[32:33] op_sel_hi:[1,0]
	v_pk_mul_f32 v[20:21], v[20:21], v[32:33] op_sel_hi:[1,0]
	v_pk_mul_f32 v[26:27], v[26:27], v[32:33] op_sel_hi:[1,0]
	v_pk_mul_f32 v[24:25], v[24:25], v[32:33] op_sel_hi:[1,0]
	v_pk_mul_f32 v[30:31], v[30:31], v[32:33] op_sel_hi:[1,0]
	v_pk_mul_f32 v[28:29], v[28:29], v[32:33] op_sel_hi:[1,0]
	v_mfma_f32_16x16x32_f16 v[16:19], v[34:37], v[50:53], v[16:19]
	s_waitcnt lgkmcnt(0)
	s_barrier
; #define LDS_BARRIER() do { asm volatile("s_waitcnt lgkmcnt(0)" ::: "memory"); __builtin_amdgcn_s_barrier(); asm volatile("" ::: "memory"); } while (0)
; #define MFMA16(a, b, c) __builtin_amdgcn_mfma_f32_16x16x32_f16((a), (b), (c), 0, 0, 0)
; __device__ __forceinline__ void phase_scan(h16* Pdn, const h16* Tg, const h16* qkg, const float* gcg, const float* betag, const float* s2g, unsigned char* ldsb) {
;     ...
;                 for (int t = 0; t < 4; ++t) {
;                     f32x4 acc = S[t] * e_last;
; #pragma unroll
;                     for (int k2 = 0; k2 < 2; ++k2) acc = MFMA16(F0[2 * t + k2], V2f[k2], acc);
;                     S[t] = acc;
;                 }
;                 __builtin_amdgcn_sched_barrier(0);
; #pragma unroll
;                 for (int t = 0; t < 4; ++t) {
;                     f32x4 acc = S[4 + t] * e_last;
; #pragma unroll
;                     for (int k2 = 0; k2 < 2; ++k2) acc = MFMA16(F1[2 * t + k2], V2f[k2], acc);
;                     S[4 + t] = acc;
;                 }
;     ...
;             }
;             LDS_BARRIER();
;         }
;         }
	s_waitcnt lgkmcnt(10)
	v_mfma_f32_16x16x32_f16 v[20:23], v[38:41], v[50:53], v[20:23]
	s_add_i32 s7, s7, 1
	s_add_i32 s12, s12, 0x40000
	s_cmp_eq_u32 s7, 64
	s_waitcnt lgkmcnt(6)
	v_mfma_f32_16x16x32_f16 v[24:27], v[58:61], v[50:53], v[24:27]
	s_waitcnt lgkmcnt(2)
	v_mfma_f32_16x16x32_f16 v[28:31], v[82:85], v[50:53], v[28:31]
	v_mfma_f32_16x16x32_f16 v[16:19], v[42:45], v[54:57], v[16:19]
	v_mfma_f32_16x16x32_f16 v[20:23], v[46:49], v[54:57], v[20:23]
	v_mfma_f32_16x16x32_f16 v[24:27], v[62:65], v[54:57], v[24:27]
	s_waitcnt lgkmcnt(0)
	v_mfma_f32_16x16x32_f16 v[28:31], v[86:89], v[54:57], v[28:31]
	s_cbranch_scc0 .LBB0_247
	s_setprio 0
	v_writelane_b32 v254, s4, 43
	s_mov_b64 s[0:1], 0
	s_nop 0
	v_writelane_b32 v254, s5, 44
	v_writelane_b32 v254, s6, 45
	v_writelane_b32 v254, s7, 46
	v_writelane_b32 v254, s8, 47
	v_writelane_b32 v254, s9, 48
	v_writelane_b32 v254, s10, 49
	v_writelane_b32 v254, s11, 50
	v_writelane_b32 v254, s12, 51
	v_writelane_b32 v254, s13, 52
	v_writelane_b32 v254, s14, 53
	v_writelane_b32 v254, s15, 54
	v_writelane_b32 v254, s16, 55
	v_writelane_b32 v254, s17, 56
	v_writelane_b32 v254, s18, 57
	v_writelane_b32 v254, s19, 58
